# w_up: workgroups with only 5 tiles start ~12us later so their epilogue store bursts interleave with the others
# baseline (speedup 1.0000x reference)
; #define PG8_LAS __attribute__((address_space(3)))
; template <class Epi, class Sched, bool ALIGN_EPI = false, bool SP2 = false>
; __device__ __forceinline__ void gemm_phase(PG8_LAS unsigned char* lds, const Gemm g, const Sched& S, const Epi& E, const int tid) {
;     ...
;         const bool has_next = S.next(ui + 1, nxt);
;     pg8::Gemm gm{A, Bt, mrows, N, K, a_rows}; pg8::StaticOrder S; S.init(mrows, N, nb, bid);
;     pg8::gemm_phase<Epi, pg8::StaticOrder, true, true>((PG8_LAS unsigned char*)lds, gm, S, E, tid);
.LBB0_619:
	s_or_b64 exec, exec, s[2:3]
	s_waitcnt lgkmcnt(0)
	s_barrier
	s_cmpk_eq_i32 s87, 0x100
	s_cbranch_scc0 .Lwup_nostag
	s_cmpk_lt_i32 s86, 0x96
	s_cbranch_scc1 .Lwup_nostag
	s_sleep 127
	s_sleep 127
	s_sleep 127
.Lwup_nostag:
	s_cmpk_lt_i32 s86, 0x596
	s_cselect_b64 s[2:3], -1, 0
	v_readfirstlane_b32 s1, v158
	s_and_b64 vcc, exec, s[2:3]
	s_cbranch_vccz .LBB0_625
	s_ashr_i32 s0, s86, 31
	s_lshr_b32 s0, s0, 29
	s_add_i32 s0, s86, s0
	s_and_b32 s4, s0, -8
	s_sub_i32 s6, s86, s4
	s_cmp_gt_i32 s6, 5
	s_mov_b64 s[4:5], -1
	s_cbranch_scc0 .LBB0_622
	s_mul_i32 s4, s6, 0xb2
	s_add_i32 s7, s4, 6
	s_mov_b64 s[4:5], 0
